# P2 work list rebalanced: the 32 workgroups that get a third compression item hand their two prep items to 64 other workgroups; EpiAct register copies removed
# speedup vs baseline: 1.0077x; 1.0018x over previous
; DI void compress_item(const Args& a, int l, int item, unsigned char* lds, int tid) {
;     ...
;     const int lane = tid & 63, wave = __builtin_amdgcn_readfirstlane(tid >> 6);
;     const int tix = item % 17, r3 = item / 17, j = r3 & 1, g = (r3 >> 1) & 1, b = r3 >> 2;
;     const float* pe = a.in[5] + ((size_t)l * 2 + j) * 2048; const float* w2 = a.in[7] + ((size_t)l * 2 + j) * 64 * 64; const float* g1 = a.in[4] + (size_t)l * 4 * 64 + 64;
;     const int r = lane & 15, kq = lane >> 4, n = 15 * tix + r;
;     const bf16_t* arow = Z1 + ((size_t)b * SEQ + 16 * n) * ZP + C_KV + j * 128 + g * 64;
;     const bf16_t* wrow = W1T + (size_t)j * 64 * 2048 + (size_t)r * 2048;
;     float* part = (float*)lds; float* hs = (float*)(lds + 32768);
;     pg8::f32x4 acc[4];
; #pragma unroll
;     for (int ct = 0; ct < 4; ++ct) acc[ct] = (pg8::f32x4){0.f, 0.f, 0.f, 0.f};
; #pragma unroll
;     for (int ks = 0; ks < 8; ++ks) { const int kk = wave * 256 + ks * 32 + kq * 8, li = kk >> 6, d0 = kk & 63; bf16x8 af;
;         if (r < 15) af = *(const bf16x8*)(arow + (size_t)li * ZP + d0);
; __global__ void __launch_bounds__(512, 2) fwd_kernel(Args a_unused) {
;     ...
;             for (int it = bid; it < 1824; it += G) {
;                 int t2 = tid; asm volatile("" : "+v"(t2));
;                 if (it < 256) sgu_item(a, l, it, lds, t2);
;                 else if (it < 768) prep_item(a, l, it - 256, lds, t2);
;                 else if (it < 1280) mix_ac_item(a, l, it - 768, t2);
;                 else compress_item(a, l, it - 1280, lds, t2);
;             }
.LBB0_299:
	v_readlane_b32 s0, v253, 15
	v_readlane_b32 s1, v253, 16
	s_andn2_b64 vcc, exec, s[0:1]
	s_barrier
	s_cbranch_vccnz .LBB0_480
	v_readlane_b32 s10, v254, 3
	v_readlane_b32 s11, v254, 4
	s_add_u32 s75, s10, 0x200000
	s_addc_u32 s69, s11, 0
	s_add_u32 s84, s10, 0x300000
	v_readlane_b32 s0, v254, 14
	s_addc_u32 s90, s11, 0
	v_readlane_b32 s1, v254, 15
	s_mov_b32 s8, s0
	s_ashr_i32 s9, s0, 31
	v_readlane_b32 s16, v253, 35
	s_lshl_b64 s[12:13], s[8:9], 1
	s_lshl_b64 s[0:1], s[8:9], 10
	v_readlane_b32 s24, v253, 43
	v_readlane_b32 s25, v253, 44
	s_add_u32 s14, s24, s0
	s_addc_u32 s15, s25, s1
	s_add_u32 s0, s10, 0x280000
	s_addc_u32 s1, s11, 0
	v_writelane_b32 v254, s0, 48
	s_add_u32 s94, s10, 0x18280000
	v_readlane_b32 s20, v253, 39
	v_readlane_b32 s22, v253, 41
	v_writelane_b32 v254, s1, 49
	s_addc_u32 s95, s11, 0
	s_mul_i32 s1, s8, 0x1800
	v_readlane_b32 s21, v253, 40
	v_readlane_b32 s23, v253, 42
	s_mul_hi_i32 s0, s8, 0x1800
	s_add_u32 s20, s22, s1
	s_addc_u32 s21, s23, s0
	s_add_u32 s22, s10, 0x7100000
	s_addc_u32 s23, s11, 0
	s_add_u32 s86, s10, 0x1c280000
	s_addc_u32 s87, s11, 0
	s_add_u32 s96, s10, 0x6100000
	s_addc_u32 s97, s11, 0
	s_lshl_b32 s0, s8, 9
	s_ashr_i32 s1, s0, 31
	v_readlane_b32 s36, v253, 51
	v_readlane_b32 s26, v253, 45
	s_lshl_b64 s[0:1], s[0:1], 2
	v_readlane_b32 s40, v253, 55
	s_mov_b32 s6, s8
	v_readlane_b32 s27, v253, 46
	v_readlane_b32 s41, v253, 56
	v_readlane_b32 s49, v254, 0
	v_readlane_b32 s50, v254, 1
	v_readlane_b32 s51, v254, 2
	s_add_u32 s26, s40, s0
	v_writelane_b32 v254, s6, 14
	v_readlane_b32 s28, v253, 47
	v_readlane_b32 s44, v253, 59
	s_addc_u32 s27, s41, s1
	v_writelane_b32 v254, s7, 15
	s_lshl_b64 s[6:7], s[8:9], 18
	v_readlane_b32 s29, v253, 48
	v_readlane_b32 s45, v253, 60
	s_add_u32 s28, s44, s0
	v_readlane_b32 s30, v253, 49
	s_addc_u32 s29, s45, s1
	v_readlane_b32 s31, v253, 50
	s_add_u32 s30, s10, 0x1e280000
	v_readlane_b32 s42, v253, 57
	s_addc_u32 s31, s11, 0
	v_readlane_b32 s17, v253, 36
	v_readlane_b32 s18, v253, 37
	v_readlane_b32 s19, v253, 38
	v_readlane_b32 s43, v253, 58
	s_add_u32 s33, s42, s6
	s_addc_u32 s16, s43, s7
	s_lshl_b32 s17, s52, 6
	s_lshl_b32 s18, s52, 7
	v_readlane_b32 s19, v253, 19
	v_readlane_b32 s24, v253, 18
	s_mov_b32 s25, s2
	v_readlane_b32 s37, v253, 52
	v_readlane_b32 s38, v253, 53
	v_readlane_b32 s39, v253, 54
	v_readlane_b32 s46, v253, 61
	v_readlane_b32 s47, v253, 62
	v_readlane_b32 s48, v253, 63
	s_mov_b32 s99, 0
	s_branch .LBB0_302
.LBB0_301:
	s_cmp_eq_u32 s99, 0
	s_cbranch_scc1 .Lp2_latch
	s_mov_b32 s25, s99
	s_mov_b32 s99, 0
.Lp2_latch:
	s_add_i32 s25, s25, s52
	s_add_i32 s24, s24, s17
	s_add_i32 s19, s19, s18
	s_cmpk_gt_i32 s25, 0x75f
	s_cbranch_scc1 .LBB0_480
	s_cmpk_gt_i32 s25, 0x71f
	s_cbranch_scc0 .LBB0_302
	s_cmp_lg_u32 s52, 0x100
	s_cbranch_scc1 .LBB0_480
.LBB0_302:
	v_mov_b32_e32 v146, v225
	s_cmp_lg_u32 s52, 0x100
	s_cbranch_scc1 .Lp2_norm
	s_cmpk_gt_i32 s25, 0x71f
	s_cbranch_scc1 .Lp2_extra
	s_and_b32 s98, s25, 0xff
	s_cmp_ge_u32 s98, 32
	s_cbranch_scc1 .Lp2_norm
	s_cmpk_gt_i32 s25, 0xff
	s_cbranch_scc0 .Lp2_norm
	s_cmpk_gt_i32 s25, 0x2ff
	s_cbranch_scc1 .Lp2_norm
	s_branch .LBB0_301
.Lp2_extra:
	s_mov_b32 s99, s25
	s_add_i32 s98, s25, 0xfffff900
	s_cmp_lt_u32 s98, 64
	s_mov_b32 s98, 0xfffffac0
	s_cselect_b32 s98, 0xfffff9e0, s98
	s_add_i32 s25, s25, s98
.Lp2_norm:
	s_cmpk_gt_i32 s25, 0xff
	s_cbranch_scc0 .LBB0_349
	s_cmpk_gt_u32 s25, 0x2ff
	s_cbranch_scc0 .LBB0_350
	s_cmpk_gt_u32 s25, 0x4ff
	s_cbranch_scc0 .LBB0_351
	s_add_i32 s0, s25, 0xfb00
	s_and_b32 s1, s0, 0xffff
	s_mul_i32 s1, s1, 0xf0f1
	s_lshr_b32 s6, s1, 20
	s_mul_i32 s6, s6, 17
	s_sub_i32 s55, s0, s6
	s_mul_i32 s8, s55, 15
	v_and_b32_e32 v32, 15, v146
	s_and_b32 s54, s8, 0xffff
	v_readlane_b32 s10, v254, 3
	s_bfe_u32 s9, s1, 0x10014
	s_lshr_b32 s53, s1, 22
	v_add_lshl_u32 v0, v32, s54, 4
	v_readlane_b32 s11, v254, 4
	v_readfirstlane_b32 s59, v146
	s_bfe_u32 s52, s1, 0x10015
	s_or_b32 s0, s12, s9
	s_mov_b32 s1, s13
	v_lshl_add_u32 v2, s53, 12, v0
	v_mov_b64_e32 v[0:1], s[10:11]
	v_readlane_b32 s36, v253, 35
	s_lshl_b64 s[6:7], s[0:1], 13
	v_mad_u64_u32 v[0:1], s[10:11], v2, s3, v[0:1]
	s_ashr_i32 s8, s59, 6
	v_readlane_b32 s46, v253, 45
	v_readlane_b32 s47, v253, 46
	s_add_u32 s10, s46, s6
	s_addc_u32 s11, s47, s7
	v_bfe_u32 v33, v146, 4, 2
	s_lshl_b32 s80, s9, 8
	v_lshl_add_u64 v[0:1], v[0:1], 0, s[80:81]
	s_lshl_b32 s80, s52, 7
	s_lshl_b32 s34, s8, 8
	v_lshlrev_b32_e32 v26, 3, v33
	v_lshl_add_u64 v[0:1], v[0:1], 0, s[80:81]
	s_mov_b64 s[6:7], 0x7101000
	v_or_b32_e32 v20, s34, v26
	v_readlane_b32 s37, v253, 36
	v_lshl_add_u64 v[28:29], v[0:1], 0, s[6:7]
	v_cmp_ne_u32_e64 s[6:7], 15, v32
	v_lshlrev_b32_e32 v30, 1, v26
	v_ashrrev_i32_e32 v21, 31, v20
	v_readlane_b32 s38, v253, 37
	v_readlane_b32 s39, v253, 38
	v_readlane_b32 s40, v253, 39
	v_readlane_b32 s41, v253, 40
	v_readlane_b32 s42, v253, 41
	v_readlane_b32 s43, v253, 42
	v_readlane_b32 s44, v253, 43
	v_readlane_b32 s45, v253, 44
	v_readlane_b32 s48, v253, 47
	v_readlane_b32 s49, v253, 48
	v_readlane_b32 s50, v253, 49
	v_readlane_b32 s51, v253, 50
	s_and_saveexec_b64 s[36:37], s[6:7]
	s_xor_b64 s[36:37], exec, s[36:37]
	s_cbranch_execz .LBB0_307
	s_lshl_b32 s35, s8, 2
	v_mov_b32_e32 v0, 0x2230
	v_mad_i64_i32 v[0:1], s[56:57], s35, v0, v[28:29]
	v_mov_b32_e32 v31, v161
	v_lshl_add_u64 v[0:1], v[0:1], 0, v[30:31]
	global_load_dwordx4 v[0:3], v[0:1], off

;     __device__ __forceinline__ void operator()(f32x4 (&acc)[2][2][4][2], const Unit& u, int wr, int wc, int fr_in, int fq_in) const {
;     ...
;             for (int m = 0; m < 4; ++m) { const int row = row0 + ai * HALF + m * 16; const f32x4 pv = *(const f32x4*)(ss + (size_t)row * 16 + 4 * fq); float sq = (pv[0] + pv[1]) + (pv[2] + pv[3]); sq += __shfl_xor(sq, 16); sq += __shfl_xor(sq, 32); const float rs = rsqrtf(sq * (1.0f / 1024.0f) + 1e-6f);
; #pragma unroll
;                 for (int bj = 0; bj < 2; ++bj)
; #pragma unroll
;                     for (int n = 0; n < 2; ++n) acc[ai][bj][m][n] = acc[ai][bj][m][n] * rs; }
;         if (fr >= 14) {
; #pragma unroll
;             for (int ai = 0; ai < 2; ++ai) { PG8_LAS float* x = xl + ((((wave * 2 + ai) * 2 + (fr - 14)) * 4 + fq) * 8); *(PG8_LAS f32x4*)x = acc[ai][0][3][0]; *(PG8_LAS f32x4*)(x + 4) = acc[ai][0][3][1]; }
;             if (wr == 1) { float* s = sb + ((size_t)(0 * 128 + u.pm) * 2 + (fr - 14)) * 2816 + cb; *(f32x4*)s = acc[1][0][3][0]; *(f32x4*)(s + 4) = acc[1][0][3][1]; } }
;         if (wr == 0 && fr < 2) { float* s = sb + ((size_t)(1 * 128 + u.pm) * 2 + fr) * 2816 + cb; *(f32x4*)s = acc[0][0][0][0]; *(f32x4*)(s + 4) = acc[0][0][0][1];
;             float* t = sb + ((size_t)(2 * 128 + u.pm) * 2 + fr) * 2816 + cb; *(f32x4*)t = acc[0][1][0][0]; *(f32x4*)(t + 4) = acc[0][1][0][1]; }
;         asm volatile("s_waitcnt lgkmcnt(0)" ::: "memory"); __builtin_amdgcn_s_barrier(); asm volatile("" ::: "memory");
; #pragma unroll
;         for (int ai = 0; ai < 2; ++ai)
; #pragma unroll
;             for (int m = 0; m < 4; ++m) {
;                 const bool skip = (ai == 0) && (m == 0) && (wr == 0) && (fr < 2);
;                 bf16_t* op = O + (size_t)(row0 + ai * HALF + m * 16) * 2816 + cb;
; #pragma unroll
;                 for (int n = 0; n < 2; ++n) { f32x4 p1, p2;
;                     if (m == 0) { const int sai = (wr == 1) ? ai : (ai > 0 ? ai - 1 : 0); const int swave = (wr ^ 1) * 4 + wc;
;                         p1 = *(const PG8_LAS f32x4*)(xl + ((((swave * 2 + sai) * 2 + 1) * 4 + fq) * 8) + 4 * n); p2 = *(const PG8_LAS f32x4*)(xl + ((((swave * 2 + sai) * 2 + (fr == 0 ? 0 : 1)) * 4 + fq) * 8) + 4 * n); }
; #pragma unroll
;                     for (int e = 0; e < 4; ++e) { const float gv = acc[ai][0][m][n][e]; const float s1 = dpp_ror<0x121>(gv), s2 = dpp_ror<0x122>(gv); float q1, q2;
.LBB0_535:
	s_or_b64 exec, exec, s[0:1]
	v_mul_f32_e32 v160, 0x4b800000, v210
	v_mov_b32_dpp v187, v148 row_ror:1 row_mask:0xf bank_mask:0xf
	v_mov_b32_dpp v191, v148 row_ror:2 row_mask:0xf bank_mask:0xf
	v_cndmask_b32_e64 v148, v210, v160, s[12:13]
	v_mov_b32_dpp v214, v150 row_ror:1 row_mask:0xf bank_mask:0xf
	v_mov_b32_dpp v234, v150 row_ror:2 row_mask:0xf bank_mask:0xf
	v_rsq_f32_e32 v150, v148
	v_mov_b64_e32 v[156:157], s[28:29]
	s_movk_i32 s0, 0x2000
	s_movk_i32 s33, 0x1600
	v_lshlrev_b64 v[158:159], 1, v[208:209]
	v_mov_b32_dpp v193, v149 row_ror:1 row_mask:0xf bank_mask:0xf
	v_mov_b32_dpp v205, v149 row_ror:2 row_mask:0xf bank_mask:0xf
	v_add_co_u32_e32 v208, vcc, s0, v198
	v_mad_i64_i32 v[148:149], s[0:1], v206, s33, v[156:157]
	v_lshl_add_u64 v[210:211], v[148:149], 0, v[158:159]
	v_mul_f32_e32 v148, 0x45800000, v150
	v_cndmask_b32_e64 v160, v150, v148, s[12:13]
	v_mov_b32_dpp v236, v151 row_ror:1 row_mask:0xf bank_mask:0xf
	v_mov_b32_dpp v235, v151 row_ror:2 row_mask:0xf bank_mask:0xf
	v_pk_mul_f32 v[148:149], v[110:111], v[160:161] op_sel_hi:[1,0]
	v_pk_mul_f32 v[150:151], v[108:109], v[160:161] op_sel_hi:[1,0]
	v_addc_co_u32_e32 v209, vcc, 0, v199, vcc
	s_nop 0
	v_mov_b32_dpp v238, v150 row_ror:1 row_mask:0xf bank_mask:0xf
	v_mov_b32_dpp v240, v151 row_ror:1 row_mask:0xf bank_mask:0xf
	v_mov_b32_dpp v242, v148 row_ror:1 row_mask:0xf bank_mask:0xf
	v_mov_b32_dpp v244, v149 row_ror:1 row_mask:0xf bank_mask:0xf
	v_mov_b32_dpp v239, v150 row_ror:2 row_mask:0xf bank_mask:0xf
	v_mov_b32_dpp v241, v151 row_ror:2 row_mask:0xf bank_mask:0xf
	v_mov_b32_dpp v243, v148 row_ror:2 row_mask:0xf bank_mask:0xf
	v_mov_b32_dpp v245, v149 row_ror:2 row_mask:0xf bank_mask:0xf
	v_cndmask_b32_e64 v207, v193, v240, s[14:15]
	v_cndmask_b32_e64 v206, v187, v238, s[68:69]
	v_cndmask_b32_e64 v237, v236, v244, s[14:15]
	v_cndmask_b32_e64 v236, v214, v242, s[68:69]
	v_cndmask_b32_e64 v213, v205, v241, s[64:65]
	v_cndmask_b32_e64 v212, v191, v239, s[66:67]
	v_cndmask_b32_e64 v235, v235, v245, s[64:65]
	v_cndmask_b32_e64 v234, v234, v243, s[66:67]
	s_movk_i32 s0, 0x5000
	v_mov_b32_dpp v187, v144 row_ror:1 row_mask:0xf bank_mask:0xf
	v_mov_b32_dpp v191, v144 row_ror:2 row_mask:0xf bank_mask:0xf
	v_mov_b32_dpp v193, v145 row_ror:1 row_mask:0xf bank_mask:0xf
	v_mov_b32_dpp v205, v145 row_ror:2 row_mask:0xf bank_mask:0xf
	v_mov_b32_dpp v214, v146 row_ror:1 row_mask:0xf bank_mask:0xf
	v_pk_mul_f32 v[144:145], v[106:107], v[160:161] op_sel_hi:[1,0]
	s_mov_b32 s71, 0x800000
	v_pk_mul_f32 v[152:153], v[116:117], v[206:207]
	v_pk_mul_f32 v[154:155], v[118:119], v[236:237]
	v_pk_fma_f32 v[152:153], v[112:113], v[212:213], v[152:153]
	v_pk_fma_f32 v[154:155], v[114:115], v[234:235], v[154:155]
	v_pk_fma_f32 v[150:151], v[150:151], v[120:121], v[152:153]
	v_pk_fma_f32 v[148:149], v[148:149], v[122:123], v[154:155]
	v_mul_f32_e32 v152, 0xbfb8aa3b, v150
	v_mul_f32_e32 v153, 0xbfb8aa3b, v151
	v_mul_f32_e32 v154, 0xbfb8aa3b, v148
	v_mul_f32_e32 v155, 0xbfb8aa3b, v149
	v_exp_f32_e32 v152, v152
	v_exp_f32_e32 v153, v153
	v_exp_f32_e32 v154, v154
	v_exp_f32_e32 v155, v155
	v_add_f32_e32 v152, 1.0, v152
	v_add_f32_e32 v153, 1.0, v153
	v_add_f32_e32 v154, 1.0, v154
	v_add_f32_e32 v155, 1.0, v155
	v_rcp_f32_e32 v152, v152
	v_rcp_f32_e32 v153, v153
	v_rcp_f32_e32 v154, v154
	v_rcp_f32_e32 v155, v155
	v_pk_mul_f32 v[206:207], v[102:103], v[160:161] op_sel_hi:[1,0]
	v_pk_mul_f32 v[212:213], v[100:101], v[160:161] op_sel_hi:[1,0]
	v_pk_mul_f32 v[150:151], v[150:151], v[152:153]
	v_pk_mul_f32 v[148:149], v[148:149], v[154:155]
	v_pk_mul_f32 v[150:151], v[212:213], v[150:151]
	v_pk_mul_f32 v[148:149], v[206:207], v[148:149]
	v_cvt_pk_bf16_f32 v150, v150, v151
	v_cvt_pk_bf16_f32 v151, v148, v149
	v_mov_b64_e32 v[12:13], v[150:151]
	v_add_co_u32_e32 v206, vcc, s0, v198
	v_mov_b32_dpp v232, v146 row_ror:2 row_mask:0xf bank_mask:0xf
	s_nop 0
	v_addc_co_u32_e32 v207, vcc, 0, v199, vcc
	v_mov_b32_dpp v234, v147 row_ror:1 row_mask:0xf bank_mask:0xf
	v_mov_b32_dpp v233, v147 row_ror:2 row_mask:0xf bank_mask:0xf
	v_pk_mul_f32 v[146:147], v[104:105], v[160:161] op_sel_hi:[1,0]
	v_mov_b32_dpp v248, v144 row_ror:1 row_mask:0xf bank_mask:0xf
	v_mov_b32_dpp v215, v145 row_ror:1 row_mask:0xf bank_mask:0xf
	v_mov_b32_dpp v236, v146 row_ror:1 row_mask:0xf bank_mask:0xf
	v_mov_b32_dpp v246, v147 row_ror:1 row_mask:0xf bank_mask:0xf
	v_mov_b32_dpp v237, v146 row_ror:2 row_mask:0xf bank_mask:0xf
	v_mov_b32_dpp v247, v147 row_ror:2 row_mask:0xf bank_mask:0xf
	v_mov_b32_dpp v249, v144 row_ror:2 row_mask:0xf bank_mask:0xf
	v_mov_b32_dpp v251, v145 row_ror:2 row_mask:0xf bank_mask:0xf
	v_cndmask_b32_e64 v213, v193, v246, s[14:15]
	v_cndmask_b32_e64 v212, v187, v236, s[68:69]
	v_cndmask_b32_e64 v235, v234, v215, s[14:15]
	v_cndmask_b32_e64 v234, v214, v248, s[68:69]
	v_cndmask_b32_e64 v231, v205, v247, s[64:65]
	v_cndmask_b32_e64 v230, v191, v237, s[66:67]
	v_cndmask_b32_e64 v233, v233, v251, s[64:65]
	v_cndmask_b32_e64 v232, v232, v249, s[66:67]
	v_mad_i64_i32 v[204:205], s[0:1], v204, s33, v[156:157]
	v_lshl_add_u64 v[204:205], v[204:205], 0, v[158:159]
	v_pk_mul_f32 v[152:153], v[72:73], v[212:213]
	v_pk_mul_f32 v[154:155], v[74:75], v[234:235]
	v_pk_fma_f32 v[148:149], v[124:125], v[230:231], v[152:153]
	v_pk_fma_f32 v[150:151], v[126:127], v[232:233], v[154:155]
	v_pk_mul_f32 v[152:153], v[98:99], v[160:161] op_sel_hi:[1,0]
	v_pk_mul_f32 v[154:155], v[96:97], v[160:161] op_sel_hi:[1,0]
	v_pk_fma_f32 v[146:147], v[146:147], v[76:77], v[148:149]
	v_pk_fma_f32 v[144:145], v[144:145], v[78:79], v[150:151]
	v_mul_f32_e32 v148, 0xbfb8aa3b, v146
	v_mul_f32_e32 v149, 0xbfb8aa3b, v147
	v_mul_f32_e32 v150, 0xbfb8aa3b, v144
;     __device__ __forceinline__ void operator()(f32x4 (&acc)[2][2][4][2], const Unit& u, int wr, int wc, int fr_in, int fq_in) const {
;     ...
;             for (int m = 0; m < 4; ++m) { const int row = row0 + ai * HALF + m * 16; const f32x4 pv = *(const f32x4*)(ss + (size_t)row * 16 + 4 * fq); float sq = (pv[0] + pv[1]) + (pv[2] + pv[3]); sq += __shfl_xor(sq, 16); sq += __shfl_xor(sq, 32); const float rs = rsqrtf(sq * (1.0f / 1024.0f) + 1e-6f);
; #pragma unroll
;                 for (int bj = 0; bj < 2; ++bj)
; #pragma unroll
;                     for (int n = 0; n < 2; ++n) acc[ai][bj][m][n] = acc[ai][bj][m][n] * rs; }
;         if (fr >= 14) {
; #pragma unroll
;             for (int ai = 0; ai < 2; ++ai) { PG8_LAS float* x = xl + ((((wave * 2 + ai) * 2 + (fr - 14)) * 4 + fq) * 8); *(PG8_LAS f32x4*)x = acc[ai][0][3][0]; *(PG8_LAS f32x4*)(x + 4) = acc[ai][0][3][1]; }
;             if (wr == 1) { float* s = sb + ((size_t)(0 * 128 + u.pm) * 2 + (fr - 14)) * 2816 + cb; *(f32x4*)s = acc[1][0][3][0]; *(f32x4*)(s + 4) = acc[1][0][3][1]; } }
;         if (wr == 0 && fr < 2) { float* s = sb + ((size_t)(1 * 128 + u.pm) * 2 + fr) * 2816 + cb; *(f32x4*)s = acc[0][0][0][0]; *(f32x4*)(s + 4) = acc[0][0][0][1];
;             float* t = sb + ((size_t)(2 * 128 + u.pm) * 2 + fr) * 2816 + cb; *(f32x4*)t = acc[0][1][0][0]; *(f32x4*)(t + 4) = acc[0][1][0][1]; }
;         asm volatile("s_waitcnt lgkmcnt(0)" ::: "memory"); __builtin_amdgcn_s_barrier(); asm volatile("" ::: "memory");
; #pragma unroll
;         for (int ai = 0; ai < 2; ++ai)
; #pragma unroll
;             for (int m = 0; m < 4; ++m) {
;                 const bool skip = (ai == 0) && (m == 0) && (wr == 0) && (fr < 2);
;                 bf16_t* op = O + (size_t)(row0 + ai * HALF + m * 16) * 2816 + cb;
; #pragma unroll
;                 for (int n = 0; n < 2; ++n) { f32x4 p1, p2;
;                     if (m == 0) { const int sai = (wr == 1) ? ai : (ai > 0 ? ai - 1 : 0); const int swave = (wr ^ 1) * 4 + wc;
;                         p1 = *(const PG8_LAS f32x4*)(xl + ((((swave * 2 + sai) * 2 + 1) * 4 + fq) * 8) + 4 * n); p2 = *(const PG8_LAS f32x4*)(xl + ((((swave * 2 + sai) * 2 + (fr == 0 ? 0 : 1)) * 4 + fq) * 8) + 4 * n); }
; #pragma unroll
;                     for (int e = 0; e < 4; ++e) { const float gv = acc[ai][0][m][n][e]; const float s1 = dpp_ror<0x121>(gv), s2 = dpp_ror<0x122>(gv); float q1, q2;
	v_mul_f32_e32 v151, 0xbfb8aa3b, v145
	v_exp_f32_e32 v148, v148
	v_exp_f32_e32 v149, v149
	v_exp_f32_e32 v150, v150
	v_exp_f32_e32 v151, v151
	v_add_f32_e32 v148, 1.0, v148
	v_add_f32_e32 v149, 1.0, v149
	v_add_f32_e32 v150, 1.0, v150
	v_add_f32_e32 v151, 1.0, v151
	v_rcp_f32_e32 v148, v148
	v_rcp_f32_e32 v149, v149
	v_rcp_f32_e32 v150, v150
	v_rcp_f32_e32 v151, v151
	v_mul_f32_e32 v160, 0x4b800000, v189
	v_pk_mul_f32 v[146:147], v[146:147], v[148:149]
	v_cndmask_b32_e64 v160, v189, v160, s[10:11]
	v_pk_mul_f32 v[144:145], v[144:145], v[150:151]
	v_pk_mul_f32 v[146:147], v[154:155], v[146:147]
	v_pk_mul_f32 v[144:145], v[152:153], v[144:145]
	v_cvt_pk_bf16_f32 v146, v146, v147
	v_cvt_pk_bf16_f32 v147, v144, v145
	v_mov_b64_e32 v[14:15], v[146:147]
	global_store_dwordx4 v[210:211], v[12:15], off
	v_rsq_f32_e32 v160, v160
	v_mov_b32_e32 v189, v188
	v_mul_f32_e32 v187, 0x45800000, v160
	v_cndmask_b32_e64 v160, v160, v187, s[10:11]
	v_pk_mul_f32 v[210:211], v[94:95], v[160:161] op_sel_hi:[1,0]
	v_pk_mul_f32 v[212:213], v[92:93], v[160:161] op_sel_hi:[1,0]
	s_mov_b32 s10, 0x800000
	v_mov_b32_dpp v234, v210 row_ror:1 row_mask:0xf bank_mask:0xf
	v_mov_b32_dpp v187, v212 row_ror:1 row_mask:0xf bank_mask:0xf
	v_mov_b32_dpp v193, v213 row_ror:1 row_mask:0xf bank_mask:0xf
	v_mov_b32_dpp v252, v211 row_ror:1 row_mask:0xf bank_mask:0xf
	v_mov_b32_dpp v191, v212 row_ror:2 row_mask:0xf bank_mask:0xf
	v_mov_b32_dpp v214, v213 row_ror:2 row_mask:0xf bank_mask:0xf
	v_mov_b32_dpp v235, v210 row_ror:2 row_mask:0xf bank_mask:0xf
	v_mov_b32_dpp v250, v211 row_ror:2 row_mask:0xf bank_mask:0xf
	v_cndmask_b32_e64 v221, v240, v193, s[14:15]
	v_cndmask_b32_e64 v220, v238, v187, s[68:69]
	v_cndmask_b32_e64 v233, v244, v252, s[14:15]
	v_cndmask_b32_e64 v232, v242, v234, s[68:69]
	v_cndmask_b32_e64 v223, v241, v214, s[64:65]
	v_cndmask_b32_e64 v222, v239, v191, s[66:67]
	v_cndmask_b32_e64 v231, v245, v250, s[64:65]
	v_cndmask_b32_e64 v230, v243, v235, s[66:67]
	v_pk_mul_f32 v[144:145], v[116:117], v[220:221]
	v_pk_mul_f32 v[146:147], v[118:119], v[232:233]
	v_pk_fma_f32 v[144:145], v[112:113], v[222:223], v[144:145]
	v_pk_fma_f32 v[146:147], v[114:115], v[230:231], v[146:147]
	v_pk_fma_f32 v[144:145], v[212:213], v[120:121], v[144:145]
	v_pk_fma_f32 v[146:147], v[210:211], v[122:123], v[146:147]
	v_mul_f32_e32 v148, 0xbfb8aa3b, v144
	v_mul_f32_e32 v149, 0xbfb8aa3b, v145
	v_mul_f32_e32 v150, 0xbfb8aa3b, v146
	v_mul_f32_e32 v151, 0xbfb8aa3b, v147
	v_exp_f32_e32 v148, v148
	v_exp_f32_e32 v149, v149
	v_exp_f32_e32 v150, v150
	v_exp_f32_e32 v151, v151
	v_add_f32_e32 v148, 1.0, v148
	v_add_f32_e32 v149, 1.0, v149
	v_add_f32_e32 v150, 1.0, v150
	v_add_f32_e32 v151, 1.0, v151
	v_rcp_f32_e32 v148, v148
	v_rcp_f32_e32 v149, v149
	v_rcp_f32_e32 v150, v150
	v_rcp_f32_e32 v151, v151
	v_pk_mul_f32 v[152:153], v[86:87], v[160:161] op_sel_hi:[1,0]
	v_pk_mul_f32 v[154:155], v[84:85], v[160:161] op_sel_hi:[1,0]
	v_pk_mul_f32 v[144:145], v[144:145], v[148:149]
	v_pk_mul_f32 v[146:147], v[146:147], v[150:151]
	v_pk_mul_f32 v[144:145], v[154:155], v[144:145]
	v_pk_mul_f32 v[146:147], v[152:153], v[146:147]
	v_cvt_pk_bf16_f32 v144, v144, v145
	v_cvt_pk_bf16_f32 v145, v146, v147
	v_mov_b64_e32 v[12:13], v[144:145]
	v_pk_mul_f32 v[210:211], v[90:91], v[160:161] op_sel_hi:[1,0]
	v_pk_mul_f32 v[212:213], v[88:89], v[160:161] op_sel_hi:[1,0]
	s_nop 0
	v_mov_b32_dpp v242, v210 row_ror:1 row_mask:0xf bank_mask:0xf
	v_mov_b32_dpp v238, v212 row_ror:1 row_mask:0xf bank_mask:0xf
	v_mov_b32_dpp v240, v213 row_ror:1 row_mask:0xf bank_mask:0xf
	v_mov_b32_dpp v244, v211 row_ror:1 row_mask:0xf bank_mask:0xf
	v_mov_b32_dpp v239, v212 row_ror:2 row_mask:0xf bank_mask:0xf
	v_mov_b32_dpp v241, v213 row_ror:2 row_mask:0xf bank_mask:0xf
	v_mov_b32_dpp v243, v210 row_ror:2 row_mask:0xf bank_mask:0xf
	v_mov_b32_dpp v245, v211 row_ror:2 row_mask:0xf bank_mask:0xf
	v_cndmask_b32_e64 v221, v246, v240, s[14:15]
	v_cndmask_b32_e64 v220, v236, v238, s[68:69]
	v_cndmask_b32_e64 v233, v215, v244, s[14:15]
	v_cndmask_b32_e64 v232, v248, v242, s[68:69]
	v_cndmask_b32_e64 v223, v247, v241, s[64:65]
	v_cndmask_b32_e64 v222, v237, v239, s[66:67]
	v_cndmask_b32_e64 v231, v251, v245, s[64:65]
	v_cndmask_b32_e64 v230, v249, v243, s[66:67]
	v_mov_b32_dpp v215, v140 row_ror:2 row_mask:0xf bank_mask:0xf
	v_pk_mul_f32 v[144:145], v[72:73], v[220:221]
	v_pk_mul_f32 v[146:147], v[74:75], v[232:233]
	v_pk_fma_f32 v[144:145], v[124:125], v[222:223], v[144:145]
	v_pk_fma_f32 v[146:147], v[126:127], v[230:231], v[146:147]
	v_pk_fma_f32 v[144:145], v[212:213], v[76:77], v[144:145]
	v_pk_fma_f32 v[146:147], v[210:211], v[78:79], v[146:147]
	v_mul_f32_e32 v148, 0xbfb8aa3b, v144
	v_mul_f32_e32 v149, 0xbfb8aa3b, v145
	v_mul_f32_e32 v150, 0xbfb8aa3b, v146
	v_mul_f32_e32 v151, 0xbfb8aa3b, v147
	v_exp_f32_e32 v148, v148
	v_exp_f32_e32 v149, v149
	v_exp_f32_e32 v150, v150
	v_exp_f32_e32 v151, v151
	v_add_f32_e32 v148, 1.0, v148
	v_add_f32_e32 v149, 1.0, v149
	v_add_f32_e32 v150, 1.0, v150
	v_add_f32_e32 v151, 1.0, v151
	v_rcp_f32_e32 v148, v148
	v_rcp_f32_e32 v149, v149
	v_rcp_f32_e32 v150, v150
	v_rcp_f32_e32 v151, v151
	v_pk_mul_f32 v[152:153], v[82:83], v[160:161] op_sel_hi:[1,0]
	v_pk_mul_f32 v[154:155], v[80:81], v[160:161] op_sel_hi:[1,0]
	v_pk_mul_f32 v[144:145], v[144:145], v[148:149]
	v_pk_mul_f32 v[146:147], v[146:147], v[150:151]
	v_pk_mul_f32 v[144:145], v[154:155], v[144:145]
	v_pk_mul_f32 v[146:147], v[152:153], v[146:147]
	v_cvt_pk_bf16_f32 v144, v144, v145
	v_cvt_pk_bf16_f32 v145, v146, v147
	v_mov_b64_e32 v[14:15], v[144:145]
	global_store_dwordx4 v[204:205], v[12:15], off
	v_mov_b32_dpp v160, v140 row_ror:1 row_mask:0xf bank_mask:0xf
;     __device__ __forceinline__ void operator()(f32x4 (&acc)[2][2][4][2], const Unit& u, int wr, int wc, int fr_in, int fq_in) const {
;     ...
;             for (int m = 0; m < 4; ++m) { const int row = row0 + ai * HALF + m * 16; const f32x4 pv = *(const f32x4*)(ss + (size_t)row * 16 + 4 * fq); float sq = (pv[0] + pv[1]) + (pv[2] + pv[3]); sq += __shfl_xor(sq, 16); sq += __shfl_xor(sq, 32); const float rs = rsqrtf(sq * (1.0f / 1024.0f) + 1e-6f);
; #pragma unroll
;                 for (int bj = 0; bj < 2; ++bj)
; #pragma unroll
;                     for (int n = 0; n < 2; ++n) acc[ai][bj][m][n] = acc[ai][bj][m][n] * rs; }
;         if (fr >= 14) {
; #pragma unroll
;             for (int ai = 0; ai < 2; ++ai) { PG8_LAS float* x = xl + ((((wave * 2 + ai) * 2 + (fr - 14)) * 4 + fq) * 8); *(PG8_LAS f32x4*)x = acc[ai][0][3][0]; *(PG8_LAS f32x4*)(x + 4) = acc[ai][0][3][1]; }
;             if (wr == 1) { float* s = sb + ((size_t)(0 * 128 + u.pm) * 2 + (fr - 14)) * 2816 + cb; *(f32x4*)s = acc[1][0][3][0]; *(f32x4*)(s + 4) = acc[1][0][3][1]; } }
;         if (wr == 0 && fr < 2) { float* s = sb + ((size_t)(1 * 128 + u.pm) * 2 + fr) * 2816 + cb; *(f32x4*)s = acc[0][0][0][0]; *(f32x4*)(s + 4) = acc[0][0][0][1];
;             float* t = sb + ((size_t)(2 * 128 + u.pm) * 2 + fr) * 2816 + cb; *(f32x4*)t = acc[0][1][0][0]; *(f32x4*)(t + 4) = acc[0][1][0][1]; }
;         asm volatile("s_waitcnt lgkmcnt(0)" ::: "memory"); __builtin_amdgcn_s_barrier(); asm volatile("" ::: "memory");
; #pragma unroll
;         for (int ai = 0; ai < 2; ++ai)
; #pragma unroll
;             for (int m = 0; m < 4; ++m) {
;                 const bool skip = (ai == 0) && (m == 0) && (wr == 0) && (fr < 2);
;                 bf16_t* op = O + (size_t)(row0 + ai * HALF + m * 16) * 2816 + cb;
; #pragma unroll
;                 for (int n = 0; n < 2; ++n) { f32x4 p1, p2;
;                     if (m == 0) { const int sai = (wr == 1) ? ai : (ai > 0 ? ai - 1 : 0); const int swave = (wr ^ 1) * 4 + wc;
;                         p1 = *(const PG8_LAS f32x4*)(xl + ((((swave * 2 + sai) * 2 + 1) * 4 + fq) * 8) + 4 * n); p2 = *(const PG8_LAS f32x4*)(xl + ((((swave * 2 + sai) * 2 + (fr == 0 ? 0 : 1)) * 4 + fq) * 8) + 4 * n); }
; #pragma unroll
;                     for (int e = 0; e < 4; ++e) { const float gv = acc[ai][0][m][n][e]; const float s1 = dpp_ror<0x121>(gv), s2 = dpp_ror<0x122>(gv); float q1, q2;
	v_mov_b32_dpp v220, v141 row_ror:1 row_mask:0xf bank_mask:0xf
	v_mov_b32_dpp v232, v142 row_ror:1 row_mask:0xf bank_mask:0xf
	v_mov_b32_dpp v233, v143 row_ror:1 row_mask:0xf bank_mask:0xf
	v_mov_b32_dpp v222, v141 row_ror:2 row_mask:0xf bank_mask:0xf
	v_mov_b32_dpp v230, v142 row_ror:2 row_mask:0xf bank_mask:0xf
	v_mov_b32_dpp v231, v143 row_ror:2 row_mask:0xf bank_mask:0xf
	v_cndmask_b32_e64 v221, v193, v220, s[14:15]
	v_cndmask_b32_e64 v220, v187, v160, s[68:69]
	v_cndmask_b32_e64 v233, v252, v233, s[14:15]
	v_cndmask_b32_e64 v232, v234, v232, s[68:69]
	v_cndmask_b32_e64 v223, v214, v222, s[64:65]
	v_cndmask_b32_e64 v222, v191, v215, s[66:67]
	v_cndmask_b32_e64 v231, v250, v231, s[64:65]
	v_cndmask_b32_e64 v230, v235, v230, s[66:67]
	v_mov_b32_e32 v204, v188
	v_mov_b32_e32 v205, v188
	v_pk_mul_f32 v[210:211], v[70:71], v[204:205]
	v_pk_mul_f32 v[212:213], v[68:69], v[188:189]
	v_mov_b32_dpp v193, v138 row_ror:1 row_mask:0xf bank_mask:0xf
	v_mov_b32_dpp v160, v136 row_ror:2 row_mask:0xf bank_mask:0xf
	v_mov_b32_dpp v187, v137 row_ror:2 row_mask:0xf bank_mask:0xf
	v_cndmask_b32_e64 v191, v241, v187, s[64:65]
	v_pk_mul_f32 v[144:145], v[116:117], v[220:221]
	v_pk_mul_f32 v[146:147], v[118:119], v[232:233]
	v_pk_fma_f32 v[144:145], v[112:113], v[222:223], v[144:145]
	v_pk_fma_f32 v[146:147], v[114:115], v[230:231], v[146:147]
	v_pk_fma_f32 v[140:141], v[140:141], v[120:121], v[144:145]
	v_pk_fma_f32 v[142:143], v[142:143], v[122:123], v[146:147]
	v_mul_f32_e32 v144, 0xbfb8aa3b, v140
	v_mul_f32_e32 v145, 0xbfb8aa3b, v141
	v_mul_f32_e32 v146, 0xbfb8aa3b, v142
	v_mul_f32_e32 v147, 0xbfb8aa3b, v143
	v_exp_f32_e32 v144, v144
	v_exp_f32_e32 v145, v145
	v_exp_f32_e32 v146, v146
	v_exp_f32_e32 v147, v147
	v_add_f32_e32 v144, 1.0, v144
	v_add_f32_e32 v145, 1.0, v145
	v_add_f32_e32 v146, 1.0, v146
	v_add_f32_e32 v147, 1.0, v147
	v_rcp_f32_e32 v144, v144
	v_rcp_f32_e32 v145, v145
	v_rcp_f32_e32 v146, v146
	v_rcp_f32_e32 v147, v147
	v_mad_i64_i32 v[148:149], s[0:1], v190, s33, v[156:157]
	v_pk_mul_f32 v[140:141], v[140:141], v[144:145]
	v_pk_mul_f32 v[142:143], v[142:143], v[146:147]
	v_pk_mul_f32 v[140:141], v[212:213], v[140:141]
	v_pk_mul_f32 v[142:143], v[210:211], v[142:143]
	v_lshl_add_u64 v[152:153], v[148:149], 0, v[158:159]
	v_cvt_pk_bf16_f32 v140, v140, v141
	v_cvt_pk_bf16_f32 v141, v142, v143
	v_mov_b64_e32 v[12:13], v[140:141]
	v_mov_b32_dpp v154, v136 row_ror:1 row_mask:0xf bank_mask:0xf
	v_mov_b32_dpp v155, v137 row_ror:1 row_mask:0xf bank_mask:0xf
	v_mov_b32_dpp v212, v139 row_ror:1 row_mask:0xf bank_mask:0xf
	v_mov_b32_dpp v210, v138 row_ror:2 row_mask:0xf bank_mask:0xf
	v_mov_b32_dpp v211, v139 row_ror:2 row_mask:0xf bank_mask:0xf
	v_cndmask_b32_e64 v155, v240, v155, s[14:15]
	v_cndmask_b32_e64 v154, v238, v154, s[68:69]
	v_cndmask_b32_e64 v213, v244, v212, s[14:15]
	v_cndmask_b32_e64 v212, v242, v193, s[68:69]
	v_cndmask_b32_e64 v190, v239, v160, s[66:67]
	v_cndmask_b32_e64 v211, v245, v211, s[64:65]
	v_cndmask_b32_e64 v210, v243, v210, s[66:67]
	v_readlane_b32 s0, v254, 52
	v_pk_mul_f32 v[140:141], v[72:73], v[154:155]
	v_pk_mul_f32 v[142:143], v[74:75], v[212:213]
	v_pk_fma_f32 v[140:141], v[124:125], v[190:191], v[140:141]
	v_pk_fma_f32 v[142:143], v[126:127], v[210:211], v[142:143]
	v_pk_fma_f32 v[136:137], v[136:137], v[76:77], v[140:141]
	v_pk_fma_f32 v[138:139], v[138:139], v[78:79], v[142:143]
	v_mul_f32_e32 v140, 0xbfb8aa3b, v136
	v_mul_f32_e32 v141, 0xbfb8aa3b, v137
	v_mul_f32_e32 v142, 0xbfb8aa3b, v138
	v_mul_f32_e32 v143, 0xbfb8aa3b, v139
	v_exp_f32_e32 v140, v140
	v_exp_f32_e32 v141, v141
	v_exp_f32_e32 v142, v142
	v_exp_f32_e32 v143, v143
	v_add_f32_e32 v140, 1.0, v140
	v_add_f32_e32 v141, 1.0, v141
	v_add_f32_e32 v142, 1.0, v142
	v_add_f32_e32 v143, 1.0, v143
	v_rcp_f32_e32 v140, v140
	v_rcp_f32_e32 v141, v141
	v_rcp_f32_e32 v142, v142
	v_rcp_f32_e32 v143, v143
	v_pk_mul_f32 v[144:145], v[66:67], v[204:205]
	v_pk_mul_f32 v[146:147], v[64:65], v[188:189]
	v_pk_mul_f32 v[136:137], v[136:137], v[140:141]
	v_pk_mul_f32 v[138:139], v[138:139], v[142:143]
	v_pk_mul_f32 v[136:137], v[146:147], v[136:137]
	v_pk_mul_f32 v[138:139], v[144:145], v[138:139]
	v_cvt_pk_bf16_f32 v136, v136, v137
	v_cvt_pk_bf16_f32 v137, v138, v139
	v_mov_b64_e32 v[14:15], v[136:137]
	global_store_dwordx4 v[152:153], v[12:15], off
	v_pk_add_f32 v[148:149], v[194:195], v[196:197]
	v_or_b32_e32 v150, s93, v183
	v_pk_fma_f32 v[188:189], v[148:149], s[80:81], v[162:163] op_sel_hi:[1,0,0]
	v_add_u32_e32 v183, s0, v181
	v_mul_f32_e32 v148, 0x4b800000, v189
	v_cmp_gt_f32_e32 vcc, s10, v189
	v_lshlrev_b32_e32 v150, 7, v150
	v_add3_u32 v181, s51, v150, v181
	v_cndmask_b32_e32 v148, v189, v148, vcc
	v_rsq_f32_e32 v151, v148
	v_mad_i64_i32 v[148:149], s[0:1], v192, s33, v[156:157]
	v_lshl_add_u64 v[190:191], v[148:149], 0, v[158:159]
	v_mul_f32_e32 v148, 0x45800000, v151
	v_cndmask_b32_e32 v160, v151, v148, vcc
	ds_read_b128 v[148:151], v183 offset:128
	ds_read_b128 v[152:155], v181
	v_pk_mul_f32 v[192:193], v[62:63], v[160:161] op_sel_hi:[1,0]
	v_pk_mul_f32 v[194:195], v[60:61], v[160:161] op_sel_hi:[1,0]
	v_cmp_gt_f32_e32 vcc, s10, v188
	v_mov_b32_dpp v204, v192 row_ror:1 row_mask:0xf bank_mask:0xf
	v_mov_b32_dpp v189, v194 row_ror:1 row_mask:0xf bank_mask:0xf
	v_mov_b32_dpp v187, v195 row_ror:1 row_mask:0xf bank_mask:0xf
	v_mov_b32_dpp v210, v193 row_ror:1 row_mask:0xf bank_mask:0xf
	v_mov_b32_dpp v196, v194 row_ror:2 row_mask:0xf bank_mask:0xf
	v_mov_b32_dpp v197, v195 row_ror:2 row_mask:0xf bank_mask:0xf
	v_mov_b32_dpp v205, v192 row_ror:2 row_mask:0xf bank_mask:0xf
	v_mov_b32_dpp v211, v193 row_ror:2 row_mask:0xf bank_mask:0xf
	s_waitcnt lgkmcnt(1)
;     __device__ __forceinline__ void operator()(f32x4 (&acc)[2][2][4][2], const Unit& u, int wr, int wc, int fr_in, int fq_in) const {
;     ...
;             for (int m = 0; m < 4; ++m) { const int row = row0 + ai * HALF + m * 16; const f32x4 pv = *(const f32x4*)(ss + (size_t)row * 16 + 4 * fq); float sq = (pv[0] + pv[1]) + (pv[2] + pv[3]); sq += __shfl_xor(sq, 16); sq += __shfl_xor(sq, 32); const float rs = rsqrtf(sq * (1.0f / 1024.0f) + 1e-6f);
; #pragma unroll
;                 for (int bj = 0; bj < 2; ++bj)
; #pragma unroll
;                     for (int n = 0; n < 2; ++n) acc[ai][bj][m][n] = acc[ai][bj][m][n] * rs; }
;         if (fr >= 14) {
; #pragma unroll
;             for (int ai = 0; ai < 2; ++ai) { PG8_LAS float* x = xl + ((((wave * 2 + ai) * 2 + (fr - 14)) * 4 + fq) * 8); *(PG8_LAS f32x4*)x = acc[ai][0][3][0]; *(PG8_LAS f32x4*)(x + 4) = acc[ai][0][3][1]; }
;             if (wr == 1) { float* s = sb + ((size_t)(0 * 128 + u.pm) * 2 + (fr - 14)) * 2816 + cb; *(f32x4*)s = acc[1][0][3][0]; *(f32x4*)(s + 4) = acc[1][0][3][1]; } }
;         if (wr == 0 && fr < 2) { float* s = sb + ((size_t)(1 * 128 + u.pm) * 2 + fr) * 2816 + cb; *(f32x4*)s = acc[0][0][0][0]; *(f32x4*)(s + 4) = acc[0][0][0][1];
;             float* t = sb + ((size_t)(2 * 128 + u.pm) * 2 + fr) * 2816 + cb; *(f32x4*)t = acc[0][1][0][0]; *(f32x4*)(t + 4) = acc[0][1][0][1]; }
;         asm volatile("s_waitcnt lgkmcnt(0)" ::: "memory"); __builtin_amdgcn_s_barrier(); asm volatile("" ::: "memory");
; #pragma unroll
;         for (int ai = 0; ai < 2; ++ai)
; #pragma unroll
;             for (int m = 0; m < 4; ++m) {
;                 const bool skip = (ai == 0) && (m == 0) && (wr == 0) && (fr < 2);
;                 bf16_t* op = O + (size_t)(row0 + ai * HALF + m * 16) * 2816 + cb;
; #pragma unroll
;                 for (int n = 0; n < 2; ++n) { f32x4 p1, p2;
;                     if (m == 0) { const int sai = (wr == 1) ? ai : (ai > 0 ? ai - 1 : 0); const int swave = (wr ^ 1) * 4 + wc;
;                         p1 = *(const PG8_LAS f32x4*)(xl + ((((swave * 2 + sai) * 2 + 1) * 4 + fq) * 8) + 4 * n); p2 = *(const PG8_LAS f32x4*)(xl + ((((swave * 2 + sai) * 2 + (fr == 0 ? 0 : 1)) * 4 + fq) * 8) + 4 * n); }
; #pragma unroll
;                     for (int e = 0; e < 4; ++e) { const float gv = acc[ai][0][m][n][e]; const float s1 = dpp_ror<0x121>(gv), s2 = dpp_ror<0x122>(gv); float q1, q2;
	v_cndmask_b32_e64 v149, v149, v187, s[14:15]
	v_cndmask_b32_e64 v148, v148, v189, s[68:69]
	v_cndmask_b32_e64 v151, v151, v210, s[14:15]
	v_cndmask_b32_e64 v150, v150, v204, s[68:69]
	s_waitcnt lgkmcnt(0)
	v_cndmask_b32_e64 v153, v153, v197, s[64:65]
	v_cndmask_b32_e64 v152, v152, v196, s[66:67]
	v_cndmask_b32_e64 v155, v155, v211, s[64:65]
	v_cndmask_b32_e64 v154, v154, v205, s[66:67]
	v_pk_mul_f32 v[136:137], v[148:149], v[116:117]
	v_pk_mul_f32 v[138:139], v[150:151], v[118:119]
	v_pk_fma_f32 v[136:137], v[152:153], v[112:113], v[136:137]
	v_pk_fma_f32 v[138:139], v[154:155], v[114:115], v[138:139]
	v_pk_fma_f32 v[136:137], v[194:195], v[120:121], v[136:137]
	v_pk_fma_f32 v[138:139], v[192:193], v[122:123], v[138:139]
	v_mul_f32_e32 v140, 0xbfb8aa3b, v136
	v_mul_f32_e32 v141, 0xbfb8aa3b, v137
	v_mul_f32_e32 v142, 0xbfb8aa3b, v138
	v_mul_f32_e32 v143, 0xbfb8aa3b, v139
	v_exp_f32_e32 v140, v140
	v_exp_f32_e32 v141, v141
	v_exp_f32_e32 v142, v142
	v_exp_f32_e32 v143, v143
	v_add_f32_e32 v140, 1.0, v140
	v_add_f32_e32 v141, 1.0, v141
	v_add_f32_e32 v142, 1.0, v142
	v_add_f32_e32 v143, 1.0, v143
	v_rcp_f32_e32 v140, v140
	v_rcp_f32_e32 v141, v141
	v_rcp_f32_e32 v142, v142
	v_rcp_f32_e32 v143, v143
	v_pk_mul_f32 v[144:145], v[54:55], v[160:161] op_sel_hi:[1,0]
	v_pk_mul_f32 v[146:147], v[52:53], v[160:161] op_sel_hi:[1,0]
	v_pk_mul_f32 v[136:137], v[136:137], v[140:141]
	v_pk_mul_f32 v[138:139], v[138:139], v[142:143]
	v_pk_mul_f32 v[136:137], v[146:147], v[136:137]
	v_pk_mul_f32 v[138:139], v[144:145], v[138:139]
	v_cvt_pk_bf16_f32 v136, v136, v137
	v_cvt_pk_bf16_f32 v137, v138, v139
	v_mov_b64_e32 v[12:13], v[136:137]
	ds_read_b128 v[148:151], v183 offset:144
	ds_read_b128 v[152:155], v181 offset:16
	v_pk_mul_f32 v[192:193], v[58:59], v[160:161] op_sel_hi:[1,0]
	v_pk_mul_f32 v[194:195], v[56:57], v[160:161] op_sel_hi:[1,0]
	s_nop 0
	v_mov_b32_dpp v220, v192 row_ror:1 row_mask:0xf bank_mask:0xf
	v_mov_b32_dpp v212, v194 row_ror:1 row_mask:0xf bank_mask:0xf
	v_mov_b32_dpp v214, v195 row_ror:1 row_mask:0xf bank_mask:0xf
	v_mov_b32_dpp v181, v193 row_ror:1 row_mask:0xf bank_mask:0xf
	v_mov_b32_dpp v213, v194 row_ror:2 row_mask:0xf bank_mask:0xf
	v_mov_b32_dpp v215, v195 row_ror:2 row_mask:0xf bank_mask:0xf
	v_mov_b32_dpp v183, v192 row_ror:2 row_mask:0xf bank_mask:0xf
	v_mov_b32_dpp v221, v193 row_ror:2 row_mask:0xf bank_mask:0xf
	s_waitcnt lgkmcnt(1)
	v_cndmask_b32_e64 v149, v149, v214, s[14:15]
	v_cndmask_b32_e64 v148, v148, v212, s[68:69]
	v_cndmask_b32_e64 v151, v151, v181, s[14:15]
	v_cndmask_b32_e64 v150, v150, v220, s[68:69]
	s_waitcnt lgkmcnt(0)
	v_cndmask_b32_e64 v153, v153, v215, s[64:65]
	v_cndmask_b32_e64 v152, v152, v213, s[66:67]
	v_cndmask_b32_e64 v155, v155, v221, s[64:65]
	v_cndmask_b32_e64 v154, v154, v183, s[66:67]
	v_pk_mul_f32 v[136:137], v[148:149], v[72:73]
	v_pk_mul_f32 v[138:139], v[150:151], v[74:75]
	v_pk_fma_f32 v[136:137], v[152:153], v[124:125], v[136:137]
	v_pk_fma_f32 v[138:139], v[154:155], v[126:127], v[138:139]
	v_pk_fma_f32 v[136:137], v[194:195], v[76:77], v[136:137]
	v_pk_fma_f32 v[138:139], v[192:193], v[78:79], v[138:139]
	v_mul_f32_e32 v140, 0xbfb8aa3b, v136
	v_mul_f32_e32 v141, 0xbfb8aa3b, v137
	v_mul_f32_e32 v142, 0xbfb8aa3b, v138
	v_mul_f32_e32 v143, 0xbfb8aa3b, v139
	v_exp_f32_e32 v140, v140
	v_exp_f32_e32 v141, v141
	v_exp_f32_e32 v142, v142
	v_exp_f32_e32 v143, v143
	v_add_f32_e32 v140, 1.0, v140
	v_add_f32_e32 v141, 1.0, v141
	v_add_f32_e32 v142, 1.0, v142
	v_add_f32_e32 v143, 1.0, v143
	v_rcp_f32_e32 v140, v140
	v_rcp_f32_e32 v141, v141
	v_rcp_f32_e32 v142, v142
	v_rcp_f32_e32 v143, v143
	v_pk_mul_f32 v[144:145], v[50:51], v[160:161] op_sel_hi:[1,0]
	v_pk_mul_f32 v[146:147], v[48:49], v[160:161] op_sel_hi:[1,0]
	v_pk_mul_f32 v[136:137], v[136:137], v[140:141]
	v_pk_mul_f32 v[138:139], v[138:139], v[142:143]
	v_pk_mul_f32 v[136:137], v[146:147], v[136:137]
	v_pk_mul_f32 v[138:139], v[144:145], v[138:139]
	v_cvt_pk_bf16_f32 v136, v136, v137
	v_cvt_pk_bf16_f32 v137, v138, v139
	v_mov_b64_e32 v[14:15], v[136:137]
	global_store_dwordx4 v[190:191], v[12:15], off
	v_mul_f32_e32 v148, 0x4b800000, v188
	v_cndmask_b32_e32 v148, v188, v148, vcc
	v_rsq_f32_e32 v150, v148
	v_mad_i64_i32 v[148:149], s[0:1], v186, s33, v[156:157]
	v_lshl_add_u64 v[148:149], v[148:149], 0, v[158:159]
	v_mul_f32_e32 v151, 0x45800000, v150
	v_cndmask_b32_e32 v150, v150, v151, vcc
	v_pk_mul_f32 v[152:153], v[46:47], v[150:151] op_sel_hi:[1,0]
	v_pk_mul_f32 v[154:155], v[44:45], v[150:151] op_sel_hi:[1,0]
	s_nop 0
	v_mov_b32_dpp v222, v152 row_ror:1 row_mask:0xf bank_mask:0xf
	v_mov_b32_dpp v151, v154 row_ror:1 row_mask:0xf bank_mask:0xf
	v_mov_b32_dpp v194, v155 row_ror:1 row_mask:0xf bank_mask:0xf
	v_mov_b32_dpp v230, v153 row_ror:1 row_mask:0xf bank_mask:0xf
	v_mov_b32_dpp v160, v154 row_ror:2 row_mask:0xf bank_mask:0xf
	v_mov_b32_dpp v195, v155 row_ror:2 row_mask:0xf bank_mask:0xf
	v_mov_b32_dpp v223, v152 row_ror:2 row_mask:0xf bank_mask:0xf
	v_mov_b32_dpp v231, v153 row_ror:2 row_mask:0xf bank_mask:0xf
	v_cndmask_b32_e64 v187, v187, v194, s[14:15]
	v_cndmask_b32_e64 v186, v189, v151, s[68:69]
	v_cndmask_b32_e64 v193, v210, v230, s[14:15]
	v_cndmask_b32_e64 v192, v204, v222, s[68:69]
	v_cndmask_b32_e64 v189, v197, v195, s[64:65]
	v_cndmask_b32_e64 v188, v196, v160, s[66:67]
	v_cndmask_b32_e64 v191, v211, v231, s[64:65]
	v_cndmask_b32_e64 v190, v205, v223, s[66:67]
	v_pk_mul_f32 v[136:137], v[116:117], v[186:187]
	v_pk_mul_f32 v[138:139], v[118:119], v[192:193]
	v_pk_fma_f32 v[136:137], v[112:113], v[188:189], v[136:137]
	v_pk_fma_f32 v[138:139], v[114:115], v[190:191], v[138:139]
	v_pk_fma_f32 v[136:137], v[154:155], v[120:121], v[136:137]
;     __device__ __forceinline__ void operator()(f32x4 (&acc)[2][2][4][2], const Unit& u, int wr, int wc, int fr_in, int fq_in) const {
;     ...
;             for (int m = 0; m < 4; ++m) { const int row = row0 + ai * HALF + m * 16; const f32x4 pv = *(const f32x4*)(ss + (size_t)row * 16 + 4 * fq); float sq = (pv[0] + pv[1]) + (pv[2] + pv[3]); sq += __shfl_xor(sq, 16); sq += __shfl_xor(sq, 32); const float rs = rsqrtf(sq * (1.0f / 1024.0f) + 1e-6f);
; #pragma unroll
;                 for (int bj = 0; bj < 2; ++bj)
; #pragma unroll
;                     for (int n = 0; n < 2; ++n) acc[ai][bj][m][n] = acc[ai][bj][m][n] * rs; }
;         if (fr >= 14) {
; #pragma unroll
;             for (int ai = 0; ai < 2; ++ai) { PG8_LAS float* x = xl + ((((wave * 2 + ai) * 2 + (fr - 14)) * 4 + fq) * 8); *(PG8_LAS f32x4*)x = acc[ai][0][3][0]; *(PG8_LAS f32x4*)(x + 4) = acc[ai][0][3][1]; }
;             if (wr == 1) { float* s = sb + ((size_t)(0 * 128 + u.pm) * 2 + (fr - 14)) * 2816 + cb; *(f32x4*)s = acc[1][0][3][0]; *(f32x4*)(s + 4) = acc[1][0][3][1]; } }
;         if (wr == 0 && fr < 2) { float* s = sb + ((size_t)(1 * 128 + u.pm) * 2 + fr) * 2816 + cb; *(f32x4*)s = acc[0][0][0][0]; *(f32x4*)(s + 4) = acc[0][0][0][1];
;             float* t = sb + ((size_t)(2 * 128 + u.pm) * 2 + fr) * 2816 + cb; *(f32x4*)t = acc[0][1][0][0]; *(f32x4*)(t + 4) = acc[0][1][0][1]; }
;         asm volatile("s_waitcnt lgkmcnt(0)" ::: "memory"); __builtin_amdgcn_s_barrier(); asm volatile("" ::: "memory");
; #pragma unroll
;         for (int ai = 0; ai < 2; ++ai)
; #pragma unroll
;             for (int m = 0; m < 4; ++m) {
;                 const bool skip = (ai == 0) && (m == 0) && (wr == 0) && (fr < 2);
;                 bf16_t* op = O + (size_t)(row0 + ai * HALF + m * 16) * 2816 + cb;
; #pragma unroll
;                 for (int n = 0; n < 2; ++n) { f32x4 p1, p2;
;                     if (m == 0) { const int sai = (wr == 1) ? ai : (ai > 0 ? ai - 1 : 0); const int swave = (wr ^ 1) * 4 + wc;
;                         p1 = *(const PG8_LAS f32x4*)(xl + ((((swave * 2 + sai) * 2 + 1) * 4 + fq) * 8) + 4 * n); p2 = *(const PG8_LAS f32x4*)(xl + ((((swave * 2 + sai) * 2 + (fr == 0 ? 0 : 1)) * 4 + fq) * 8) + 4 * n); }
; #pragma unroll
;                     for (int e = 0; e < 4; ++e) { const float gv = acc[ai][0][m][n][e]; const float s1 = dpp_ror<0x121>(gv), s2 = dpp_ror<0x122>(gv); float q1, q2;
	v_pk_fma_f32 v[138:139], v[152:153], v[122:123], v[138:139]
	v_mul_f32_e32 v140, 0xbfb8aa3b, v136
	v_mul_f32_e32 v141, 0xbfb8aa3b, v137
	v_mul_f32_e32 v142, 0xbfb8aa3b, v138
	v_mul_f32_e32 v143, 0xbfb8aa3b, v139
	v_exp_f32_e32 v140, v140
	v_exp_f32_e32 v141, v141
	v_exp_f32_e32 v142, v142
	v_exp_f32_e32 v143, v143
	v_add_f32_e32 v140, 1.0, v140
	v_add_f32_e32 v141, 1.0, v141
	v_add_f32_e32 v142, 1.0, v142
	v_add_f32_e32 v143, 1.0, v143
	v_rcp_f32_e32 v140, v140
	v_rcp_f32_e32 v141, v141
	v_rcp_f32_e32 v142, v142
	v_rcp_f32_e32 v143, v143
	v_pk_mul_f32 v[144:145], v[38:39], v[150:151] op_sel_hi:[1,0]
	v_pk_mul_f32 v[146:147], v[36:37], v[150:151] op_sel_hi:[1,0]
	v_pk_mul_f32 v[136:137], v[136:137], v[140:141]
	v_pk_mul_f32 v[138:139], v[138:139], v[142:143]
	v_pk_mul_f32 v[136:137], v[146:147], v[136:137]
	v_pk_mul_f32 v[138:139], v[144:145], v[138:139]
	v_cvt_pk_bf16_f32 v136, v136, v137
	v_cvt_pk_bf16_f32 v137, v138, v139
	v_mov_b64_e32 v[12:13], v[136:137]
	v_pk_mul_f32 v[152:153], v[42:43], v[150:151] op_sel_hi:[1,0]
	v_pk_mul_f32 v[154:155], v[40:41], v[150:151] op_sel_hi:[1,0]
	s_nop 0
	v_mov_b32_dpp v210, v152 row_ror:1 row_mask:0xf bank_mask:0xf
	v_mov_b32_dpp v196, v154 row_ror:1 row_mask:0xf bank_mask:0xf
	v_mov_b32_dpp v204, v155 row_ror:1 row_mask:0xf bank_mask:0xf
	v_mov_b32_dpp v232, v153 row_ror:1 row_mask:0xf bank_mask:0xf
	v_mov_b32_dpp v197, v154 row_ror:2 row_mask:0xf bank_mask:0xf
	v_mov_b32_dpp v205, v155 row_ror:2 row_mask:0xf bank_mask:0xf
	v_mov_b32_dpp v211, v152 row_ror:2 row_mask:0xf bank_mask:0xf
	v_mov_b32_dpp v233, v153 row_ror:2 row_mask:0xf bank_mask:0xf
	v_cndmask_b32_e64 v187, v214, v204, s[14:15]
	v_cndmask_b32_e64 v186, v212, v196, s[68:69]
	v_cndmask_b32_e64 v193, v181, v232, s[14:15]
	v_cndmask_b32_e64 v192, v220, v210, s[68:69]
	v_cndmask_b32_e64 v189, v215, v205, s[64:65]
	v_cndmask_b32_e64 v188, v213, v197, s[66:67]
	v_cndmask_b32_e64 v191, v221, v233, s[64:65]
	v_cndmask_b32_e64 v190, v183, v211, s[66:67]
	v_pk_mul_f32 v[136:137], v[72:73], v[186:187]
	v_pk_mul_f32 v[138:139], v[74:75], v[192:193]
	v_pk_fma_f32 v[136:137], v[124:125], v[188:189], v[136:137]
	v_pk_fma_f32 v[138:139], v[126:127], v[190:191], v[138:139]
	v_pk_fma_f32 v[136:137], v[154:155], v[76:77], v[136:137]
	v_pk_fma_f32 v[138:139], v[152:153], v[78:79], v[138:139]
	v_mul_f32_e32 v140, 0xbfb8aa3b, v136
	v_mul_f32_e32 v141, 0xbfb8aa3b, v137
	v_mul_f32_e32 v142, 0xbfb8aa3b, v138
	v_mul_f32_e32 v143, 0xbfb8aa3b, v139
	v_exp_f32_e32 v140, v140
	v_exp_f32_e32 v141, v141
	v_exp_f32_e32 v142, v142
	v_exp_f32_e32 v143, v143
	v_add_f32_e32 v140, 1.0, v140
	v_add_f32_e32 v141, 1.0, v141
	v_add_f32_e32 v142, 1.0, v142
	v_add_f32_e32 v143, 1.0, v143
	v_rcp_f32_e32 v140, v140
	v_rcp_f32_e32 v141, v141
	v_rcp_f32_e32 v142, v142
	v_rcp_f32_e32 v143, v143
	v_pk_mul_f32 v[144:145], v[34:35], v[150:151] op_sel_hi:[1,0]
	v_pk_mul_f32 v[146:147], v[32:33], v[150:151] op_sel_hi:[1,0]
	v_pk_mul_f32 v[136:137], v[136:137], v[140:141]
	v_pk_mul_f32 v[138:139], v[138:139], v[142:143]
	v_pk_mul_f32 v[136:137], v[146:147], v[136:137]
	v_pk_mul_f32 v[138:139], v[144:145], v[138:139]
	v_cvt_pk_bf16_f32 v136, v136, v137
	v_cvt_pk_bf16_f32 v137, v138, v139
	v_mov_b64_e32 v[14:15], v[136:137]
	global_store_dwordx4 v[148:149], v[12:15], off
	v_mul_f32_e32 v148, 0x4b800000, v185
	v_cndmask_b32_e64 v148, v185, v148, s[8:9]
	v_rsq_f32_e32 v150, v148
	v_mad_i64_i32 v[148:149], s[0:1], v182, s33, v[156:157]
	v_lshl_add_u64 v[148:149], v[148:149], 0, v[158:159]
	v_mul_f32_e32 v152, 0x45800000, v150
	v_cndmask_b32_e64 v150, v150, v152, s[8:9]
	v_pk_mul_f32 v[152:153], v[30:31], v[150:151] op_sel_hi:[1,0]
	v_pk_mul_f32 v[154:155], v[28:29], v[150:151] op_sel_hi:[1,0]
	v_mov_b32_e32 v185, v184
	v_mov_b32_dpp v213, v152 row_ror:1 row_mask:0xf bank_mask:0xf
	v_mov_b32_dpp v181, v154 row_ror:1 row_mask:0xf bank_mask:0xf
	v_mov_b32_dpp v193, v155 row_ror:1 row_mask:0xf bank_mask:0xf
	v_mov_b32_dpp v215, v153 row_ror:1 row_mask:0xf bank_mask:0xf
	v_mov_b32_dpp v192, v154 row_ror:2 row_mask:0xf bank_mask:0xf
	v_mov_b32_dpp v212, v155 row_ror:2 row_mask:0xf bank_mask:0xf
	v_mov_b32_dpp v214, v152 row_ror:2 row_mask:0xf bank_mask:0xf
	v_mov_b32_dpp v220, v153 row_ror:2 row_mask:0xf bank_mask:0xf
	v_cndmask_b32_e64 v183, v194, v193, s[14:15]
	v_cndmask_b32_e64 v182, v151, v181, s[68:69]
	v_cndmask_b32_e64 v191, v230, v215, s[14:15]
	v_cndmask_b32_e64 v190, v222, v213, s[68:69]
	v_cndmask_b32_e64 v187, v195, v212, s[64:65]
	v_cndmask_b32_e64 v186, v160, v192, s[66:67]
	v_cndmask_b32_e64 v189, v231, v220, s[64:65]
	v_cndmask_b32_e64 v188, v223, v214, s[66:67]
	v_pk_mul_f32 v[136:137], v[116:117], v[182:183]
	v_pk_mul_f32 v[138:139], v[118:119], v[190:191]
	v_pk_fma_f32 v[136:137], v[112:113], v[186:187], v[136:137]
	v_pk_fma_f32 v[138:139], v[114:115], v[188:189], v[138:139]
	v_pk_fma_f32 v[136:137], v[154:155], v[120:121], v[136:137]
	v_pk_fma_f32 v[138:139], v[152:153], v[122:123], v[138:139]
	v_mul_f32_e32 v140, 0xbfb8aa3b, v136
	v_mul_f32_e32 v141, 0xbfb8aa3b, v137
	v_mul_f32_e32 v142, 0xbfb8aa3b, v138
	v_mul_f32_e32 v143, 0xbfb8aa3b, v139
	v_exp_f32_e32 v140, v140
	v_exp_f32_e32 v141, v141
	v_exp_f32_e32 v142, v142
	v_exp_f32_e32 v143, v143
	v_add_f32_e32 v140, 1.0, v140
	v_add_f32_e32 v141, 1.0, v141
	v_add_f32_e32 v142, 1.0, v142
	v_add_f32_e32 v143, 1.0, v143
	v_rcp_f32_e32 v140, v140
	v_rcp_f32_e32 v141, v141
	v_rcp_f32_e32 v142, v142
	v_rcp_f32_e32 v143, v143
	v_pk_mul_f32 v[144:145], v[22:23], v[150:151] op_sel_hi:[1,0]
	v_pk_mul_f32 v[146:147], v[20:21], v[150:151] op_sel_hi:[1,0]
	v_pk_mul_f32 v[136:137], v[136:137], v[140:141]
	v_pk_mul_f32 v[138:139], v[138:139], v[142:143]
;     __device__ __forceinline__ void operator()(f32x4 (&acc)[2][2][4][2], const Unit& u, int wr, int wc, int fr_in, int fq_in) const {
;     ...
;             for (int m = 0; m < 4; ++m) { const int row = row0 + ai * HALF + m * 16; const f32x4 pv = *(const f32x4*)(ss + (size_t)row * 16 + 4 * fq); float sq = (pv[0] + pv[1]) + (pv[2] + pv[3]); sq += __shfl_xor(sq, 16); sq += __shfl_xor(sq, 32); const float rs = rsqrtf(sq * (1.0f / 1024.0f) + 1e-6f);
; #pragma unroll
;                 for (int bj = 0; bj < 2; ++bj)
; #pragma unroll
;                     for (int n = 0; n < 2; ++n) acc[ai][bj][m][n] = acc[ai][bj][m][n] * rs; }
;         if (fr >= 14) {
; #pragma unroll
;             for (int ai = 0; ai < 2; ++ai) { PG8_LAS float* x = xl + ((((wave * 2 + ai) * 2 + (fr - 14)) * 4 + fq) * 8); *(PG8_LAS f32x4*)x = acc[ai][0][3][0]; *(PG8_LAS f32x4*)(x + 4) = acc[ai][0][3][1]; }
;             if (wr == 1) { float* s = sb + ((size_t)(0 * 128 + u.pm) * 2 + (fr - 14)) * 2816 + cb; *(f32x4*)s = acc[1][0][3][0]; *(f32x4*)(s + 4) = acc[1][0][3][1]; } }
;         if (wr == 0 && fr < 2) { float* s = sb + ((size_t)(1 * 128 + u.pm) * 2 + fr) * 2816 + cb; *(f32x4*)s = acc[0][0][0][0]; *(f32x4*)(s + 4) = acc[0][0][0][1];
;             float* t = sb + ((size_t)(2 * 128 + u.pm) * 2 + fr) * 2816 + cb; *(f32x4*)t = acc[0][1][0][0]; *(f32x4*)(t + 4) = acc[0][1][0][1]; }
;         asm volatile("s_waitcnt lgkmcnt(0)" ::: "memory"); __builtin_amdgcn_s_barrier(); asm volatile("" ::: "memory");
; #pragma unroll
;         for (int ai = 0; ai < 2; ++ai)
; #pragma unroll
;             for (int m = 0; m < 4; ++m) {
;                 const bool skip = (ai == 0) && (m == 0) && (wr == 0) && (fr < 2);
;                 bf16_t* op = O + (size_t)(row0 + ai * HALF + m * 16) * 2816 + cb;
; #pragma unroll
;                 for (int n = 0; n < 2; ++n) { f32x4 p1, p2;
;                     if (m == 0) { const int sai = (wr == 1) ? ai : (ai > 0 ? ai - 1 : 0); const int swave = (wr ^ 1) * 4 + wc;
;                         p1 = *(const PG8_LAS f32x4*)(xl + ((((swave * 2 + sai) * 2 + 1) * 4 + fq) * 8) + 4 * n); p2 = *(const PG8_LAS f32x4*)(xl + ((((swave * 2 + sai) * 2 + (fr == 0 ? 0 : 1)) * 4 + fq) * 8) + 4 * n); }
; #pragma unroll
;                     for (int e = 0; e < 4; ++e) { const float gv = acc[ai][0][m][n][e]; const float s1 = dpp_ror<0x121>(gv), s2 = dpp_ror<0x122>(gv); float q1, q2;
	v_pk_mul_f32 v[136:137], v[146:147], v[136:137]
	v_pk_mul_f32 v[138:139], v[144:145], v[138:139]
	v_cvt_pk_bf16_f32 v136, v136, v137
	v_cvt_pk_bf16_f32 v137, v138, v139
	v_mov_b64_e32 v[12:13], v[136:137]
	v_pk_mul_f32 v[152:153], v[26:27], v[150:151] op_sel_hi:[1,0]
	v_pk_mul_f32 v[154:155], v[24:25], v[150:151] op_sel_hi:[1,0]
	s_nop 0
	v_mov_b32_dpp v222, v152 row_ror:1 row_mask:0xf bank_mask:0xf
	v_mov_b32_dpp v160, v154 row_ror:1 row_mask:0xf bank_mask:0xf
	v_mov_b32_dpp v195, v155 row_ror:1 row_mask:0xf bank_mask:0xf
	v_mov_b32_dpp v230, v153 row_ror:1 row_mask:0xf bank_mask:0xf
	v_mov_b32_dpp v194, v154 row_ror:2 row_mask:0xf bank_mask:0xf
	v_mov_b32_dpp v221, v155 row_ror:2 row_mask:0xf bank_mask:0xf
	v_mov_b32_dpp v223, v152 row_ror:2 row_mask:0xf bank_mask:0xf
	v_mov_b32_dpp v231, v153 row_ror:2 row_mask:0xf bank_mask:0xf
	v_cndmask_b32_e64 v183, v204, v195, s[14:15]
	v_cndmask_b32_e64 v182, v196, v160, s[68:69]
	v_cndmask_b32_e64 v191, v232, v230, s[14:15]
	v_cndmask_b32_e64 v190, v210, v222, s[68:69]
	v_cndmask_b32_e64 v187, v205, v221, s[64:65]
	v_cndmask_b32_e64 v186, v197, v194, s[66:67]
	v_cndmask_b32_e64 v189, v233, v231, s[64:65]
	v_cndmask_b32_e64 v188, v211, v223, s[66:67]
	v_pk_mul_f32 v[136:137], v[72:73], v[182:183]
	v_pk_mul_f32 v[138:139], v[74:75], v[190:191]
	v_pk_fma_f32 v[136:137], v[124:125], v[186:187], v[136:137]
	v_pk_fma_f32 v[138:139], v[126:127], v[188:189], v[138:139]
	v_pk_fma_f32 v[136:137], v[154:155], v[76:77], v[136:137]
	v_pk_fma_f32 v[138:139], v[152:153], v[78:79], v[138:139]
	v_mul_f32_e32 v140, 0xbfb8aa3b, v136
	v_mul_f32_e32 v141, 0xbfb8aa3b, v137
	v_mul_f32_e32 v142, 0xbfb8aa3b, v138
	v_mul_f32_e32 v143, 0xbfb8aa3b, v139
	v_exp_f32_e32 v140, v140
	v_exp_f32_e32 v141, v141
	v_exp_f32_e32 v142, v142
	v_exp_f32_e32 v143, v143
	v_add_f32_e32 v140, 1.0, v140
	v_add_f32_e32 v141, 1.0, v141
	v_add_f32_e32 v142, 1.0, v142
	v_add_f32_e32 v143, 1.0, v143
	v_rcp_f32_e32 v140, v140
	v_rcp_f32_e32 v141, v141
	v_rcp_f32_e32 v142, v142
	v_rcp_f32_e32 v143, v143
	v_pk_mul_f32 v[144:145], v[18:19], v[150:151] op_sel_hi:[1,0]
	v_pk_mul_f32 v[146:147], v[16:17], v[150:151] op_sel_hi:[1,0]
	v_pk_mul_f32 v[136:137], v[136:137], v[140:141]
	v_pk_mul_f32 v[138:139], v[138:139], v[142:143]
	v_pk_mul_f32 v[136:137], v[146:147], v[136:137]
	v_pk_mul_f32 v[138:139], v[144:145], v[138:139]
	v_cvt_pk_bf16_f32 v136, v136, v137
	v_cvt_pk_bf16_f32 v137, v138, v139
	v_mov_b64_e32 v[14:15], v[136:137]
	global_store_dwordx4 v[148:149], v[12:15], off
	v_mov_b32_dpp v154, v132 row_ror:1 row_mask:0xf bank_mask:0xf
	v_mov_b32_dpp v155, v133 row_ror:1 row_mask:0xf bank_mask:0xf
	v_mov_b32_dpp v188, v134 row_ror:1 row_mask:0xf bank_mask:0xf
	v_mov_b32_dpp v189, v135 row_ror:1 row_mask:0xf bank_mask:0xf
	v_mov_b32_dpp v182, v132 row_ror:2 row_mask:0xf bank_mask:0xf
	v_mov_b32_dpp v183, v133 row_ror:2 row_mask:0xf bank_mask:0xf
	v_mov_b32_dpp v186, v134 row_ror:2 row_mask:0xf bank_mask:0xf
	v_mov_b32_dpp v187, v135 row_ror:2 row_mask:0xf bank_mask:0xf
	v_cndmask_b32_e64 v155, v193, v155, s[14:15]
	v_cndmask_b32_e64 v154, v181, v154, s[68:69]
	v_cndmask_b32_e64 v189, v215, v189, s[14:15]
	v_cndmask_b32_e64 v188, v213, v188, s[68:69]
	v_cndmask_b32_e64 v183, v212, v183, s[64:65]
	v_cndmask_b32_e64 v182, v192, v182, s[66:67]
	v_cndmask_b32_e64 v187, v220, v187, s[64:65]
	v_cndmask_b32_e64 v186, v214, v186, s[66:67]
	v_mov_b32_e32 v148, v184
	v_mov_b32_e32 v149, v184
	v_pk_mul_f32 v[150:151], v[6:7], v[148:149]
	v_pk_mul_f32 v[152:153], v[4:5], v[184:185]
	v_pk_mul_f32 v[136:137], v[116:117], v[154:155]
	v_pk_mul_f32 v[138:139], v[118:119], v[188:189]
	v_pk_fma_f32 v[136:137], v[112:113], v[182:183], v[136:137]
	v_pk_fma_f32 v[138:139], v[114:115], v[186:187], v[138:139]
	v_pk_fma_f32 v[132:133], v[132:133], v[120:121], v[136:137]
	v_pk_fma_f32 v[134:135], v[134:135], v[122:123], v[138:139]
	v_mul_f32_e32 v136, 0xbfb8aa3b, v132
	v_mul_f32_e32 v137, 0xbfb8aa3b, v133
	v_mul_f32_e32 v138, 0xbfb8aa3b, v134
	v_mul_f32_e32 v139, 0xbfb8aa3b, v135
	v_exp_f32_e32 v136, v136
	v_exp_f32_e32 v137, v137
	v_exp_f32_e32 v138, v138
	v_exp_f32_e32 v139, v139
	v_add_f32_e32 v136, 1.0, v136
	v_add_f32_e32 v137, 1.0, v137
	v_add_f32_e32 v138, 1.0, v138
	v_add_f32_e32 v139, 1.0, v139
	v_rcp_f32_e32 v136, v136
	v_rcp_f32_e32 v137, v137
	v_rcp_f32_e32 v138, v138
	v_rcp_f32_e32 v139, v139
	v_mad_i64_i32 v[140:141], s[0:1], v180, s33, v[156:157]
	v_pk_mul_f32 v[132:133], v[132:133], v[136:137]
	v_pk_mul_f32 v[134:135], v[134:135], v[138:139]
	v_pk_mul_f32 v[132:133], v[152:153], v[132:133]
	v_pk_mul_f32 v[134:135], v[150:151], v[134:135]
	v_lshl_add_u64 v[144:145], v[140:141], 0, v[158:159]
	v_cvt_pk_bf16_f32 v132, v132, v133
	v_cvt_pk_bf16_f32 v133, v134, v135
	v_mov_b64_e32 v[12:13], v[132:133]
	v_mov_b32_dpp v146, v128 row_ror:1 row_mask:0xf bank_mask:0xf
	v_mov_b32_dpp v147, v129 row_ror:1 row_mask:0xf bank_mask:0xf
	v_mov_b32_dpp v154, v130 row_ror:1 row_mask:0xf bank_mask:0xf
	v_mov_b32_dpp v155, v131 row_ror:1 row_mask:0xf bank_mask:0xf
	v_mov_b32_dpp v150, v128 row_ror:2 row_mask:0xf bank_mask:0xf
	v_mov_b32_dpp v151, v129 row_ror:2 row_mask:0xf bank_mask:0xf
	v_mov_b32_dpp v152, v130 row_ror:2 row_mask:0xf bank_mask:0xf
	v_mov_b32_dpp v153, v131 row_ror:2 row_mask:0xf bank_mask:0xf
	v_cndmask_b32_e64 v147, v195, v147, s[14:15]
	v_cndmask_b32_e64 v146, v160, v146, s[68:69]
	v_cndmask_b32_e64 v155, v230, v155, s[14:15]
	v_cndmask_b32_e64 v154, v222, v154, s[68:69]
	v_cndmask_b32_e64 v151, v221, v151, s[64:65]
	v_cndmask_b32_e64 v150, v194, v150, s[66:67]
	v_cndmask_b32_e64 v153, v231, v153, s[64:65]
	v_cndmask_b32_e64 v152, v223, v152, s[66:67]
	s_mov_b64 s[0:1], 0
	v_pk_mul_f32 v[132:133], v[72:73], v[146:147]
	v_pk_mul_f32 v[134:135], v[74:75], v[154:155]
	v_pk_fma_f32 v[132:133], v[124:125], v[150:151], v[132:133]
	v_pk_fma_f32 v[134:135], v[126:127], v[152:153], v[134:135]
	v_pk_fma_f32 v[128:129], v[128:129], v[76:77], v[132:133]
	v_pk_fma_f32 v[130:131], v[130:131], v[78:79], v[134:135]
	v_mul_f32_e32 v132, 0xbfb8aa3b, v128
	v_mul_f32_e32 v133, 0xbfb8aa3b, v129
	v_mul_f32_e32 v134, 0xbfb8aa3b, v130
	v_mul_f32_e32 v135, 0xbfb8aa3b, v131
	v_exp_f32_e32 v132, v132
	v_exp_f32_e32 v133, v133
	v_exp_f32_e32 v134, v134
	v_exp_f32_e32 v135, v135
	v_add_f32_e32 v132, 1.0, v132
	v_add_f32_e32 v133, 1.0, v133
	v_add_f32_e32 v134, 1.0, v134
	v_add_f32_e32 v135, 1.0, v135
	v_rcp_f32_e32 v132, v132
	v_rcp_f32_e32 v133, v133
	v_rcp_f32_e32 v134, v134
	v_rcp_f32_e32 v135, v135
	v_pk_mul_f32 v[136:137], v[2:3], v[148:149]
	v_pk_mul_f32 v[138:139], v[0:1], v[184:185]
	v_pk_mul_f32 v[128:129], v[128:129], v[132:133]
	v_pk_mul_f32 v[130:131], v[130:131], v[134:135]
	v_pk_mul_f32 v[128:129], v[138:139], v[128:129]
	v_pk_mul_f32 v[130:131], v[136:137], v[130:131]
	v_cvt_pk_bf16_f32 v128, v128, v129
	v_cvt_pk_bf16_f32 v129, v130, v131
	v_mov_b64_e32 v[14:15], v[128:129]
	global_store_dwordx4 v[144:145], v[12:15], off
